# v23 + prologue w_in conversion: the 31 remaining per-row gain loads issued together with the first (one wait) instead of sixteen serialized load->wait->multiply rounds
# baseline (speedup 1.0000x reference)
.LBB0_129:
	s_andn2_b64 vcc, exec, s[18:19]
	s_mov_b32 s17, 0
	s_cbranch_vccnz .LBB0_155
	v_readlane_b32 s68, v252, 1
	v_readlane_b32 s74, v252, 7
	v_readlane_b32 s75, v252, 8
	s_add_u32 s20, s74, s0
	s_addc_u32 s21, s75, s1
	s_lshl_b32 s0, s2, 10
	s_ashr_i32 s1, s0, 31
	v_readlane_b32 s72, v252, 5
	s_lshl_b64 s[0:1], s[0:1], 2
	v_readlane_b32 s73, v252, 6
	s_add_u32 s18, s72, s0
	s_addc_u32 s19, s73, s1
	s_add_i32 s0, s15, 0xf880
	s_lshr_b32 s0, s0, 1
	s_and_b32 s22, s0, 0x7fc0
	s_lshl_b32 s0, s15, 5
	s_and_b32 s17, s0, 0xfe0
	s_lshl_b32 s0, s17, 2
	s_add_u32 s0, s20, s0
	v_or_b32_e32 v64, s22, v0
	s_addc_u32 s1, s21, 0
	v_mov_b32_e32 v3, v16
	v_lshl_add_u64 v[6:7], s[0:1], 0, v[2:3]
	v_lshlrev_b32_e32 v8, 14, v64
	v_mov_b32_e32 v9, v16
	v_lshl_add_u64 v[6:7], v[6:7], 0, v[8:9]
	v_add_co_u32_e32 v8, vcc, s10, v6
	global_load_dword v60, v[6:7], off
	s_nop 0
	v_addc_co_u32_e32 v9, vcc, 0, v7, vcc
	global_load_dword v61, v[8:9], off
	v_add_co_u32_e32 v8, vcc, s11, v6
	s_mov_b32 s0, 0x40000
	s_nop 0
	v_addc_co_u32_e32 v9, vcc, 0, v7, vcc
	global_load_dword v62, v[8:9], off
	v_add_co_u32_e32 v8, vcc, s28, v6
	v_readlane_b32 s8, v248, 44
	s_nop 0
	v_addc_co_u32_e32 v9, vcc, 0, v7, vcc
	global_load_dword v63, v[8:9], off
	v_add_co_u32_e32 v8, vcc, s29, v6
	v_readlane_b32 s9, v248, 45
	s_nop 0
	v_addc_co_u32_e32 v9, vcc, 0, v7, vcc
	global_load_dword v56, v[8:9], off
	v_add_co_u32_e32 v8, vcc, s30, v6
	v_readlane_b32 s69, v252, 2
	s_nop 0
	v_addc_co_u32_e32 v9, vcc, 0, v7, vcc
	global_load_dword v57, v[8:9], off
	v_add_co_u32_e32 v8, vcc, s33, v6
	v_readlane_b32 s70, v252, 3
	s_nop 0
	v_addc_co_u32_e32 v9, vcc, 0, v7, vcc
	global_load_dword v58, v[8:9], off
	v_add_co_u32_e32 v8, vcc, s34, v6
	v_readlane_b32 s71, v252, 4
	s_nop 0
	v_addc_co_u32_e32 v9, vcc, 0, v7, vcc
	global_load_dword v59, v[8:9], off
	v_add_co_u32_e32 v8, vcc, s0, v6
	s_mov_b32 s0, 0x48000
	s_nop 0
	v_addc_co_u32_e32 v9, vcc, 0, v7, vcc
	global_load_dword v52, v[8:9], off
	v_add_co_u32_e32 v8, vcc, s0, v6
	s_mov_b32 s0, 0x50000
	s_nop 0
	v_addc_co_u32_e32 v9, vcc, 0, v7, vcc
	global_load_dword v53, v[8:9], off
	v_add_co_u32_e32 v8, vcc, s0, v6
	s_mov_b32 s0, 0x58000
	s_nop 0
	v_addc_co_u32_e32 v9, vcc, 0, v7, vcc
	global_load_dword v54, v[8:9], off
	v_add_co_u32_e32 v8, vcc, s0, v6
	s_mov_b32 s0, 0x60000
	s_nop 0
	v_addc_co_u32_e32 v9, vcc, 0, v7, vcc
	global_load_dword v55, v[8:9], off
	v_add_co_u32_e32 v8, vcc, s0, v6
	s_mov_b32 s0, 0x68000
	s_nop 0
	v_addc_co_u32_e32 v9, vcc, 0, v7, vcc
	global_load_dword v48, v[8:9], off
	v_add_co_u32_e32 v8, vcc, s0, v6
	s_mov_b32 s0, 0x70000
	s_nop 0
	v_addc_co_u32_e32 v9, vcc, 0, v7, vcc
	global_load_dword v49, v[8:9], off
	v_add_co_u32_e32 v8, vcc, s0, v6
	s_mov_b32 s0, 0x78000
	s_nop 0
	v_addc_co_u32_e32 v9, vcc, 0, v7, vcc
	global_load_dword v50, v[8:9], off
	v_add_co_u32_e32 v8, vcc, s0, v6
	s_mov_b32 s0, 0x80000
	s_nop 0
	v_addc_co_u32_e32 v9, vcc, 0, v7, vcc
	global_load_dword v51, v[8:9], off
	v_add_co_u32_e32 v8, vcc, s0, v6
	s_mov_b32 s0, 0x88000
	s_nop 0
	v_addc_co_u32_e32 v9, vcc, 0, v7, vcc
	global_load_dword v44, v[8:9], off
	v_add_co_u32_e32 v8, vcc, s0, v6
	s_mov_b32 s0, 0x90000
	s_nop 0
	v_addc_co_u32_e32 v9, vcc, 0, v7, vcc
	global_load_dword v45, v[8:9], off
	v_add_co_u32_e32 v8, vcc, s0, v6
	s_mov_b32 s0, 0x98000
	s_nop 0
	v_addc_co_u32_e32 v9, vcc, 0, v7, vcc
	global_load_dword v46, v[8:9], off
	v_add_co_u32_e32 v8, vcc, s0, v6
	s_mov_b32 s0, 0xa0000
	s_nop 0
	v_addc_co_u32_e32 v9, vcc, 0, v7, vcc
	global_load_dword v47, v[8:9], off
	v_add_co_u32_e32 v8, vcc, s0, v6
	s_mov_b32 s0, 0xa8000
	s_nop 0
	v_addc_co_u32_e32 v9, vcc, 0, v7, vcc
	global_load_dword v39, v[8:9], off
	v_add_co_u32_e32 v8, vcc, s0, v6
	s_mov_b32 s0, 0xb0000
	s_nop 0
	v_addc_co_u32_e32 v9, vcc, 0, v7, vcc
	global_load_dword v41, v[8:9], off
	v_add_co_u32_e32 v8, vcc, s0, v6
	s_mov_b32 s0, 0xb8000
	s_nop 0
	v_addc_co_u32_e32 v9, vcc, 0, v7, vcc
	global_load_dword v42, v[8:9], off
	v_add_co_u32_e32 v8, vcc, s0, v6
	s_mov_b32 s0, 0xc0000
	s_nop 0
	v_addc_co_u32_e32 v9, vcc, 0, v7, vcc
	global_load_dword v43, v[8:9], off
	v_add_co_u32_e32 v8, vcc, s0, v6
	s_mov_b32 s0, 0xc8000
	s_nop 0
	v_addc_co_u32_e32 v9, vcc, 0, v7, vcc
	v_add_co_u32_e32 v66, vcc, s0, v6
	s_mov_b32 s0, 0xd0000
	s_nop 0
	v_addc_co_u32_e32 v67, vcc, 0, v7, vcc
	global_load_dword v9, v[8:9], off
	v_readlane_b32 s76, v252, 9
	global_load_dword v37, v[66:67], off
	v_add_co_u32_e32 v66, vcc, s0, v6
	s_mov_b32 s0, 0xd8000
	s_nop 0
	v_addc_co_u32_e32 v67, vcc, 0, v7, vcc
	global_load_dword v38, v[66:67], off
	v_add_co_u32_e32 v66, vcc, s0, v6
	s_mov_b32 s0, 0xe0000
	s_nop 0
	v_addc_co_u32_e32 v67, vcc, 0, v7, vcc
	global_load_dword v40, v[66:67], off
	v_add_co_u32_e32 v66, vcc, s0, v6
	v_readlane_b32 s77, v252, 10
	s_nop 0
	v_addc_co_u32_e32 v67, vcc, 0, v7, vcc
	global_load_dword v3, v[66:67], off
	v_add_co_u32_e32 v66, vcc, 0xe8000, v6
	v_readlane_b32 s78, v252, 11
	s_nop 0
	v_addc_co_u32_e32 v67, vcc, 0, v7, vcc
	global_load_dword v5, v[66:67], off
	v_add_co_u32_e32 v66, vcc, 0xf0000, v6
	v_readlane_b32 s79, v252, 12
	s_nop 0
	v_addc_co_u32_e32 v67, vcc, 0, v7, vcc
	v_add_co_u32_e32 v6, vcc, 0xf8000, v6
	v_readlane_b32 s80, v252, 13
	s_nop 0
	v_addc_co_u32_e32 v7, vcc, 0, v7, vcc
	global_load_dword v6, v[6:7], off
	v_cndmask_b32_e64 v7, 0, 1, s[8:9]
	global_load_dword v8, v[66:67], off
	v_cmp_ne_u32_e64 s[0:1], 1, v7
	s_andn2_b64 vcc, exec, s[8:9]
	v_add_lshl_u32 v7, s22, v0, 2
	v_readlane_b32 s81, v252, 14
	v_readlane_b32 s82, v252, 15
	v_readlane_b32 s83, v252, 16
	s_cbranch_vccnz .LBB0_197
	v_lshlrev_b32_e32 v64, 2, v64
	global_load_dword v101, v7, s[18:19] offset:8
	global_load_dword v102, v7, s[18:19] offset:16
	global_load_dword v103, v7, s[18:19] offset:24
	global_load_dword v104, v7, s[18:19] offset:32
	global_load_dword v105, v7, s[18:19] offset:40
	global_load_dword v106, v7, s[18:19] offset:48
	global_load_dword v107, v7, s[18:19] offset:56
	global_load_dword v108, v7, s[18:19] offset:64
	global_load_dword v109, v7, s[18:19] offset:72
	global_load_dword v110, v7, s[18:19] offset:80
	global_load_dword v111, v7, s[18:19] offset:88
	global_load_dword v112, v7, s[18:19] offset:96
	global_load_dword v113, v7, s[18:19] offset:104
	global_load_dword v114, v7, s[18:19] offset:112
	global_load_dword v115, v7, s[18:19] offset:120
	global_load_dword v116, v7, s[18:19] offset:128
	global_load_dword v117, v7, s[18:19] offset:136
	global_load_dword v118, v7, s[18:19] offset:144
	global_load_dword v119, v7, s[18:19] offset:152
	global_load_dword v120, v7, s[18:19] offset:160
	global_load_dword v121, v7, s[18:19] offset:168
	global_load_dword v122, v7, s[18:19] offset:176
	global_load_dword v123, v7, s[18:19] offset:184
	global_load_dword v124, v7, s[18:19] offset:192
	global_load_dword v125, v7, s[18:19] offset:200
	global_load_dword v126, v7, s[18:19] offset:208
	global_load_dword v127, v7, s[18:19] offset:216
	global_load_dword v128, v7, s[18:19] offset:224
	global_load_dword v129, v7, s[18:19] offset:232
	global_load_dword v130, v7, s[18:19] offset:240
	global_load_dword v131, v7, s[18:19] offset:248
	global_load_dword v64, v64, s[18:19]
	s_waitcnt vmcnt(0)
	v_mov_b32_e32 v65, v101
	s_waitcnt vmcnt(1)
	v_mul_f32_e32 v64, v60, v64
	ds_write_b32 v29, v64
	s_waitcnt vmcnt(0)
	v_mul_f32_e32 v64, v61, v65
	v_add_u32_e32 v65, v10, v18
	ds_write_b32 v65, v64
	v_mov_b32_e32 v64, v102
	v_mov_b32_e32 v65, v103
	s_waitcnt vmcnt(1)
	v_mul_f32_e32 v64, v62, v64
	s_cbranch_execnz .LBB0_133

.LBB0_133:
	s_waitcnt vmcnt(31)
	v_add_u32_e32 v60, v10, v19
	s_waitcnt vmcnt(0)
	v_mul_f32_e32 v61, v63, v65
	s_and_b64 vcc, exec, s[0:1]
	ds_write2_b32 v60, v64, v61 offset1:66
	s_cbranch_vccnz .LBB0_198
	v_mov_b32_e32 v60, v104
	v_mov_b32_e32 v61, v105
	v_add_u32_e32 v62, v10, v20
	s_waitcnt vmcnt(1)
	v_mul_f32_e32 v60, v56, v60
	s_waitcnt vmcnt(0)
	v_mul_f32_e32 v61, v57, v61
	ds_write2_b32 v62, v60, v61 offset1:66
	v_mov_b32_e32 v60, v106
	v_mov_b32_e32 v61, v107
	s_waitcnt vmcnt(1)
	v_mul_f32_e32 v60, v58, v60
	s_cbranch_execnz .LBB0_136

.LBB0_136:
	v_add_u32_e32 v56, v10, v21
	s_waitcnt vmcnt(0)
	v_mul_f32_e32 v57, v59, v61
	s_and_b64 vcc, exec, s[0:1]
	ds_write2_b32 v56, v60, v57 offset1:66
	s_cbranch_vccnz .LBB0_199
	v_mov_b32_e32 v56, v108
	v_mov_b32_e32 v57, v109
	v_add_u32_e32 v58, v10, v22
	s_waitcnt vmcnt(1)
	v_mul_f32_e32 v56, v52, v56
	s_waitcnt vmcnt(0)
	v_mul_f32_e32 v57, v53, v57
	ds_write2_b32 v58, v56, v57 offset1:66
	v_mov_b32_e32 v56, v110
	v_mov_b32_e32 v57, v111
	s_waitcnt vmcnt(1)
	v_mul_f32_e32 v56, v54, v56
	s_cbranch_execnz .LBB0_139

.LBB0_139:
	v_add_u32_e32 v52, v10, v23
	s_waitcnt vmcnt(0)
	v_mul_f32_e32 v53, v55, v57
	s_and_b64 vcc, exec, s[0:1]
	ds_write2_b32 v52, v56, v53 offset1:66
	s_cbranch_vccnz .LBB0_200
	v_mov_b32_e32 v52, v112
	v_mov_b32_e32 v53, v113
	v_add_u32_e32 v54, v10, v24
	s_waitcnt vmcnt(1)
	v_mul_f32_e32 v52, v48, v52
	s_waitcnt vmcnt(0)
	v_mul_f32_e32 v53, v49, v53
	ds_write2_b32 v54, v52, v53 offset1:66
	v_mov_b32_e32 v52, v114
	v_mov_b32_e32 v53, v115
	s_waitcnt vmcnt(1)
	v_mul_f32_e32 v52, v50, v52
	s_cbranch_execnz .LBB0_142

.LBB0_142:
	v_add_u32_e32 v48, v10, v25
	s_waitcnt vmcnt(0)
	v_mul_f32_e32 v49, v51, v53
	s_and_b64 vcc, exec, s[0:1]
	ds_write2_b32 v48, v52, v49 offset1:66
	s_cbranch_vccnz .LBB0_201
	v_mov_b32_e32 v48, v116
	v_mov_b32_e32 v49, v117
	v_add_u32_e32 v50, v10, v26
	s_waitcnt vmcnt(1)
	v_mul_f32_e32 v48, v44, v48
	s_waitcnt vmcnt(0)
	v_mul_f32_e32 v49, v45, v49
	ds_write2_b32 v50, v48, v49 offset1:66
	v_mov_b32_e32 v48, v118
	v_mov_b32_e32 v49, v119
	s_waitcnt vmcnt(1)
	v_mul_f32_e32 v48, v46, v48
	s_cbranch_execnz .LBB0_145

.LBB0_145:
	v_add_u32_e32 v44, v10, v27
	s_waitcnt vmcnt(0)
	v_mul_f32_e32 v45, v47, v49
	s_and_b64 vcc, exec, s[0:1]
	ds_write2_b32 v44, v48, v45 offset1:66
	s_cbranch_vccnz .LBB0_202
	v_mov_b32_e32 v44, v120
	v_mov_b32_e32 v45, v121
	v_add_u32_e32 v46, v10, v28
	s_waitcnt vmcnt(1)
	v_mul_f32_e32 v44, v39, v44
	s_waitcnt vmcnt(0)
	v_mul_f32_e32 v45, v41, v45
	ds_write2_b32 v46, v44, v45 offset1:66
	v_mov_b32_e32 v44, v122
	v_mov_b32_e32 v45, v123
	s_waitcnt vmcnt(1)
	v_mul_f32_e32 v44, v42, v44
	s_cbranch_execnz .LBB0_148

.LBB0_148:
	v_add_u32_e32 v39, v10, v28
	s_waitcnt vmcnt(0)
	v_mul_f32_e32 v41, v43, v45
	ds_write2_b32 v39, v44, v41 offset0:132 offset1:198
	s_and_b64 vcc, exec, s[0:1]
	v_add_u32_e32 v41, 0x400, v39
	s_cbranch_vccnz .LBB0_203
	v_mov_b32_e32 v42, v124
	v_mov_b32_e32 v43, v125
	s_waitcnt vmcnt(1)
	v_mul_f32_e32 v42, v9, v42
	s_waitcnt vmcnt(0)
	v_mul_f32_e32 v43, v37, v43
	ds_write2_b32 v41, v42, v43 offset0:8 offset1:74
	v_mov_b32_e32 v42, v126
	v_mov_b32_e32 v43, v127
	s_waitcnt vmcnt(1)
	v_mul_f32_e32 v42, v38, v42
	s_cbranch_execnz .LBB0_151

.LBB0_151:
	s_waitcnt vmcnt(0)
	v_mul_f32_e32 v9, v40, v43
	ds_write2_b32 v41, v42, v9 offset0:140 offset1:206
	s_and_b64 vcc, exec, s[0:1]
	v_add_u32_e32 v9, 0x800, v39
	s_cbranch_vccnz .LBB0_204
	v_mov_b32_e32 v37, v128
	v_mov_b32_e32 v38, v129
	s_waitcnt vmcnt(1)
	v_mul_f32_e32 v37, v3, v37
	s_waitcnt vmcnt(0)
	v_mul_f32_e32 v38, v5, v38
	ds_write2_b32 v9, v37, v38 offset0:16 offset1:82
	v_mov_b32_e32 v37, v130
	s_waitcnt vmcnt(0)
	v_mul_f32_e32 v37, v8, v37
	v_mov_b32_e32 v7, v131
	s_cbranch_execnz .LBB0_154
